# P11: s_setprio 1 raised right behind the loop-top barrier (covers the first K fragment reads)
# baseline (speedup 1.0000x reference)
.Lst1_a:
.LBB0_1233:
	s_waitcnt vmcnt(6)
	s_waitcnt lgkmcnt(0)
	s_barrier
	s_setprio 1
	v_lshl_add_u32 v254, s4, 14, v217
	v_add_u32_e32 v255, v254, v225
	ds_read_b128 v[228:231], v255
	ds_read_b128 v[232:235], v255 offset:8192
	v_add_u32_e32 v255, v254, v224
	ds_read_b128 v[236:239], v255
	ds_read_b128 v[240:243], v255 offset:8192
	s_add_i32 s5, s4, 1
	s_cmp_lg_u32 s4, 2
	s_waitcnt lgkmcnt(2)
	v_add_u32_e32 v255, v254, v223
	ds_read_b128 v[246:249], v255
	ds_read_b128 v[250:253], v255 offset:8192
	v_mfma_f32_32x32x16_bf16 v[130:145], v[232:235], v[190:193], 0
	v_mfma_f32_32x32x16_bf16 v[146:161], v[228:231], v[190:193], 0
	s_waitcnt lgkmcnt(2)
	v_add_u32_e32 v255, v254, v222
	ds_read_b128 v[228:231], v255
	ds_read_b128 v[232:235], v255 offset:8192
	v_mfma_f32_32x32x16_bf16 v[130:145], v[240:243], v[186:189], v[130:145]
	v_mfma_f32_32x32x16_bf16 v[146:161], v[236:239], v[186:189], v[146:161]
	s_waitcnt lgkmcnt(2)
	v_add_u32_e32 v255, v254, v221
	ds_read_b128 v[236:239], v255
	ds_read_b128 v[240:243], v255 offset:8192
	v_mfma_f32_32x32x16_bf16 v[130:145], v[250:253], v[182:185], v[130:145]
	v_mfma_f32_32x32x16_bf16 v[146:161], v[246:249], v[182:185], v[146:161]
	s_waitcnt lgkmcnt(2)
	v_add_u32_e32 v255, v254, v220
	ds_read_b128 v[246:249], v255
	ds_read_b128 v[250:253], v255 offset:8192
	v_mfma_f32_32x32x16_bf16 v[130:145], v[232:235], v[178:181], v[130:145]
	v_mfma_f32_32x32x16_bf16 v[146:161], v[228:231], v[178:181], v[146:161]
	s_waitcnt lgkmcnt(2)
	v_add_u32_e32 v255, v254, v219
	ds_read_b128 v[228:231], v255
	ds_read_b128 v[232:235], v255 offset:8192
	v_mfma_f32_32x32x16_bf16 v[130:145], v[240:243], v[174:177], v[130:145]
	v_mfma_f32_32x32x16_bf16 v[146:161], v[236:239], v[174:177], v[146:161]
	s_waitcnt lgkmcnt(2)
	v_add_u32_e32 v255, v254, v218
	ds_read_b128 v[236:239], v255
	ds_read_b128 v[240:243], v255 offset:8192
	v_mfma_f32_32x32x16_bf16 v[130:145], v[250:253], v[170:173], v[130:145]
	v_mfma_f32_32x32x16_bf16 v[146:161], v[246:249], v[170:173], v[146:161]
	s_waitcnt lgkmcnt(2)
	v_mfma_f32_32x32x16_bf16 v[130:145], v[232:235], v[166:169], v[130:145]
	v_mfma_f32_32x32x16_bf16 v[146:161], v[228:231], v[166:169], v[146:161]
	s_waitcnt lgkmcnt(0)
	v_mfma_f32_32x32x16_bf16 v[130:145], v[240:243], v[162:165], v[130:145]
	v_mfma_f32_32x32x16_bf16 v[146:161], v[236:239], v[162:165], v[146:161]
	s_setprio 0
	s_nop 10
	v_fmamk_f32 v138, v138, 0x3e0293ee, v215
	v_fmamk_f32 v139, v139, 0x3e0293ee, v215
	v_fmamk_f32 v140, v140, 0x3e0293ee, v215
	v_fmamk_f32 v141, v141, 0x3e0293ee, v215
	v_fmamk_f32 v142, v142, 0x3e0293ee, v215
	v_exp_f32_e32 v226, v138
	v_fmamk_f32 v130, v130, 0x3e0293ee, v215
	v_fmamk_f32 v138, v155, 0x3e0293ee, v215
	v_exp_f32_e32 v155, v139
	v_fmamk_f32 v139, v156, 0x3e0293ee, v215
	v_exp_f32_e32 v156, v140
	v_fmamk_f32 v140, v157, 0x3e0293ee, v215
	v_exp_f32_e32 v157, v141
	v_fmamk_f32 v141, v158, 0x3e0293ee, v215
	v_exp_f32_e32 v158, v142
	v_fmamk_f32 v142, v159, 0x3e0293ee, v215
	v_fmamk_f32 v146, v146, 0x3e0293ee, v215
	v_exp_f32_e32 v159, v142
	v_fmamk_f32 v142, v143, 0x3e0293ee, v215
	v_exp_f32_e32 v146, v146
	v_fmamk_f32 v147, v147, 0x3e0293ee, v215
	v_exp_f32_e32 v227, v142
	v_fmamk_f32 v142, v160, 0x3e0293ee, v215
	v_exp_f32_e32 v147, v147
	v_fmamk_f32 v148, v148, 0x3e0293ee, v215
	v_exp_f32_e32 v160, v142
	v_fmamk_f32 v142, v144, 0x3e0293ee, v215
	v_exp_f32_e32 v148, v148
	v_fmamk_f32 v149, v149, 0x3e0293ee, v215
	v_exp_f32_e32 v228, v142
	v_fmamk_f32 v142, v161, 0x3e0293ee, v215
	v_exp_f32_e32 v149, v149
	v_fmamk_f32 v150, v150, 0x3e0293ee, v215
	v_exp_f32_e32 v161, v142
	v_fmamk_f32 v142, v145, 0x3e0293ee, v215
	v_exp_f32_e32 v150, v150
	v_fmamk_f32 v151, v151, 0x3e0293ee, v215
	v_exp_f32_e32 v229, v142
	v_add_f32_e32 v142, 0, v146
	v_exp_f32_e32 v151, v151
	v_fmamk_f32 v152, v152, 0x3e0293ee, v215
	v_add_f32_e32 v142, v147, v142
	v_exp_f32_e32 v152, v152
	v_fmamk_f32 v153, v153, 0x3e0293ee, v215
	v_add_f32_e32 v142, v148, v142
	v_exp_f32_e32 v153, v153
	v_fmamk_f32 v154, v154, 0x3e0293ee, v215
	v_add_f32_e32 v142, v149, v142
	v_exp_f32_e32 v154, v154
	v_add_f32_e32 v142, v150, v142
	v_exp_f32_e32 v138, v138
	v_add_f32_e32 v142, v151, v142
	v_exp_f32_e32 v139, v139
	v_add_f32_e32 v142, v152, v142
	v_exp_f32_e32 v140, v140
	v_add_f32_e32 v142, v153, v142
	v_exp_f32_e32 v141, v141
	v_add_f32_e32 v142, v154, v142
	v_add_f32_e32 v142, v138, v142
	v_add_f32_e32 v142, v139, v142
	v_add_f32_e32 v142, v140, v142
	v_exp_f32_e32 v130, v130
	v_fmamk_f32 v131, v131, 0x3e0293ee, v215
	v_add_f32_e32 v142, v141, v142
	v_exp_f32_e32 v131, v131
	v_fmamk_f32 v132, v132, 0x3e0293ee, v215
	v_add_f32_e32 v142, v159, v142
	v_exp_f32_e32 v132, v132
	v_fmamk_f32 v133, v133, 0x3e0293ee, v215
	v_add_f32_e32 v142, v160, v142
	v_exp_f32_e32 v133, v133
	v_fmamk_f32 v134, v134, 0x3e0293ee, v215
	v_add_f32_e32 v142, v161, v142
	v_exp_f32_e32 v134, v134
	v_fmamk_f32 v135, v135, 0x3e0293ee, v215
	v_add_f32_e32 v142, v130, v142
	v_exp_f32_e32 v135, v135
	v_fmamk_f32 v136, v136, 0x3e0293ee, v215
	v_add_f32_e32 v142, v131, v142
	v_exp_f32_e32 v136, v136
	v_fmamk_f32 v137, v137, 0x3e0293ee, v215
	v_add_f32_e32 v142, v132, v142
	v_exp_f32_e32 v137, v137
	v_add_f32_e32 v142, v133, v142
	v_add_f32_e32 v142, v134, v142
	v_add_f32_e32 v142, v135, v142
	v_add_f32_e32 v142, v136, v142
	v_add_f32_e32 v142, v137, v142
	v_add_f32_e32 v142, v226, v142
	v_add_f32_e32 v142, v155, v142
	v_add_f32_e32 v142, v156, v142
	v_add_f32_e32 v142, v157, v142
	v_add_f32_e32 v142, v158, v142
	v_add_f32_e32 v142, v227, v142
	v_add_f32_e32 v142, v228, v142
	v_add_f32_e32 v142, v229, v142
	v_mov_b32_e32 v143, v142
	s_nop 1
	v_permlane32_swap_b32_e32 v142, v143
	v_add_f32_e32 v142, v142, v143
	v_add_f32_e32 v211, v211, v142
	v_cvt_pk_bf16_f32 v142, v146, v147
	v_cvt_pk_bf16_f32 v143, v148, v149
	v_cvt_pk_bf16_f32 v144, v150, v151
	v_cvt_pk_bf16_f32 v145, v152, v153
	s_nop 0
	v_permlane32_swap_b32_e32 v142, v144
	v_permlane32_swap_b32_e32 v143, v145
	v_lshl_add_u32 v146, s4, 15, v216
	v_cvt_pk_bf16_f32 v138, v154, v138
	v_cvt_pk_bf16_f32 v139, v139, v140
	v_cvt_pk_bf16_f32 v140, v141, v159
	v_cvt_pk_bf16_f32 v141, v160, v161
	v_cvt_pk_bf16_f32 v130, v130, v131
	v_cvt_pk_bf16_f32 v131, v132, v133
	v_cvt_pk_bf16_f32 v132, v134, v135
	v_cvt_pk_bf16_f32 v133, v136, v137
	v_cvt_pk_bf16_f32 v134, v226, v155
	v_cvt_pk_bf16_f32 v135, v156, v157
	v_cvt_pk_bf16_f32 v136, v158, v227
	v_cvt_pk_bf16_f32 v137, v228, v229
	v_add_u32_e32 v152, 0xc000, v146
	s_waitcnt vmcnt(0)
	s_barrier
	s_add_i32 s98, s4, -1
	s_cmp_eq_u32 s4, 0
	s_cselect_b32 s98, 2, s98
	s_lshl_b32 s99, s98, 14
	s_add_i32 s99, s90, s99
	s_lshl_b32 s98, s98, 15
	s_add_i32 s98, s90, s98
	v_lshl_add_u64 v[236:237], v[194:195], 0, s[2:3]
	s_mov_b32 m0, s99
	s_nop 0
	global_load_lds_dwordx4 v[236:237], off
	v_lshl_add_u64 v[236:237], v[196:197], 0, s[2:3]
	s_add_i32 m0, s99, 0x2000
	s_nop 0
	global_load_lds_dwordx4 v[236:237], off
	v_lshl_add_u64 v[236:237], v[198:199], 0, s[2:3]
	s_add_i32 m0, s98, 0xc000
	s_nop 0
	global_load_lds_dwordx4 v[236:237], off
	v_lshl_add_u64 v[236:237], v[200:201], 0, s[2:3]
	s_add_i32 m0, s98, 0xe000
	s_nop 0
	global_load_lds_dwordx4 v[236:237], off
	v_lshl_add_u64 v[236:237], v[202:203], 0, s[2:3]
	s_add_i32 m0, s98, 0x10000
	s_nop 0
	global_load_lds_dwordx4 v[236:237], off
	v_lshl_add_u64 v[236:237], v[208:209], 0, s[2:3]
	s_add_i32 m0, s98, 0x12000
	s_nop 0
	global_load_lds_dwordx4 v[236:237], off
	s_cmp_lg_u32 s4, 2
	ds_read_b64_tr_b16 v[148:149], v146 offset:49152
	ds_read_b64_tr_b16 v[150:151], v146 offset:53248
	ds_read_b64_tr_b16 v[154:155], v146 offset:57344
	ds_read_b64_tr_b16 v[156:157], v146 offset:61440
	ds_read_b64_tr_b16 v[158:159], v152 offset:16384
	ds_read_b64_tr_b16 v[160:161], v152 offset:20480
	ds_read_b64_tr_b16 v[232:233], v152 offset:24576
	ds_read_b64_tr_b16 v[234:235], v152 offset:28672
	ds_read_b64_tr_b16 v[236:237], v146 offset:49664
	ds_read_b64_tr_b16 v[238:239], v146 offset:53760
	ds_read_b64_tr_b16 v[240:241], v146 offset:57856
	ds_read_b64_tr_b16 v[242:243], v146 offset:61952
	s_setprio 1
	s_waitcnt lgkmcnt(8)
	ds_read_b64_tr_b16 v[246:247], v152 offset:16896
	ds_read_b64_tr_b16 v[248:249], v152 offset:20992
	ds_read_b64_tr_b16 v[250:251], v152 offset:25088
	ds_read_b64_tr_b16 v[252:253], v152 offset:29184
	v_mfma_f32_32x32x16_bf16 v[114:129], v[142:145], v[148:151], v[114:129]
	v_permlane32_swap_b32_e32 v138, v140
	v_permlane32_swap_b32_e32 v139, v141
	v_permlane32_swap_b32_e32 v130, v132
	v_permlane32_swap_b32_e32 v131, v133
	v_mfma_f32_32x32x16_bf16 v[114:129], v[138:141], v[154:157], v[114:129]
	v_permlane32_swap_b32_e32 v134, v136
	v_permlane32_swap_b32_e32 v135, v137
	s_cselect_b32 s4, s5, 0
	s_add_u32 s2, s2, 0x100000
	s_addc_u32 s3, s3, 0
	s_waitcnt lgkmcnt(8)
	ds_read_b64_tr_b16 v[148:149], v146 offset:50176
	ds_read_b64_tr_b16 v[150:151], v146 offset:54272
	ds_read_b64_tr_b16 v[154:155], v146 offset:58368
	ds_read_b64_tr_b16 v[156:157], v146 offset:62464
	v_mfma_f32_32x32x16_bf16 v[114:129], v[130:133], v[158:161], v[114:129]
	v_mfma_f32_32x32x16_bf16 v[114:129], v[134:137], v[232:235], v[114:129]
	s_cmp_eq_u32 s2, 0x2200000
	s_waitcnt lgkmcnt(8)
	ds_read_b64_tr_b16 v[158:159], v152 offset:17408
	ds_read_b64_tr_b16 v[160:161], v152 offset:21504
	ds_read_b64_tr_b16 v[232:233], v152 offset:25600
	ds_read_b64_tr_b16 v[234:235], v152 offset:29696
	v_mfma_f32_32x32x16_bf16 v[98:113], v[142:145], v[236:239], v[98:113]
	v_mfma_f32_32x32x16_bf16 v[98:113], v[138:141], v[240:243], v[98:113]
	s_waitcnt lgkmcnt(8)
	ds_read_b64_tr_b16 v[236:237], v146 offset:50688
	ds_read_b64_tr_b16 v[238:239], v146 offset:54784
	ds_read_b64_tr_b16 v[240:241], v146 offset:58880
	ds_read_b64_tr_b16 v[242:243], v146 offset:62976
	v_mfma_f32_32x32x16_bf16 v[98:113], v[130:133], v[246:249], v[98:113]
	v_mfma_f32_32x32x16_bf16 v[98:113], v[134:137], v[250:253], v[98:113]
	s_waitcnt lgkmcnt(8)
	ds_read_b64_tr_b16 v[246:247], v152 offset:17920
	ds_read_b64_tr_b16 v[248:249], v152 offset:22016
	ds_read_b64_tr_b16 v[250:251], v152 offset:26112
	ds_read_b64_tr_b16 v[252:253], v152 offset:30208
	v_mfma_f32_32x32x16_bf16 v[82:97], v[142:145], v[148:151], v[82:97]
	v_mfma_f32_32x32x16_bf16 v[82:97], v[138:141], v[154:157], v[82:97]
	s_waitcnt lgkmcnt(8)
	ds_read_b64_tr_b16 v[148:149], v146 offset:51200
	ds_read_b64_tr_b16 v[150:151], v146 offset:55296
	ds_read_b64_tr_b16 v[154:155], v146 offset:59392
	ds_read_b64_tr_b16 v[156:157], v146 offset:63488
	v_mfma_f32_32x32x16_bf16 v[82:97], v[130:133], v[158:161], v[82:97]
	v_mfma_f32_32x32x16_bf16 v[82:97], v[134:137], v[232:235], v[82:97]
	s_waitcnt lgkmcnt(8)
	ds_read_b64_tr_b16 v[158:159], v152 offset:18432
	ds_read_b64_tr_b16 v[160:161], v152 offset:22528
	ds_read_b64_tr_b16 v[232:233], v152 offset:26624
	ds_read_b64_tr_b16 v[234:235], v152 offset:30720
	v_mfma_f32_32x32x16_bf16 v[66:81], v[142:145], v[236:239], v[66:81]
	v_mfma_f32_32x32x16_bf16 v[66:81], v[138:141], v[240:243], v[66:81]
	s_waitcnt lgkmcnt(8)
	ds_read_b64_tr_b16 v[236:237], v146 offset:51712
	ds_read_b64_tr_b16 v[238:239], v146 offset:55808
	ds_read_b64_tr_b16 v[240:241], v146 offset:59904
	ds_read_b64_tr_b16 v[242:243], v146 offset:64000
	v_mfma_f32_32x32x16_bf16 v[66:81], v[130:133], v[246:249], v[66:81]
	v_mfma_f32_32x32x16_bf16 v[66:81], v[134:137], v[250:253], v[66:81]
	s_waitcnt lgkmcnt(8)
	ds_read_b64_tr_b16 v[246:247], v152 offset:18944
	ds_read_b64_tr_b16 v[248:249], v152 offset:23040
	ds_read_b64_tr_b16 v[250:251], v152 offset:27136
	ds_read_b64_tr_b16 v[252:253], v152 offset:31232
	v_mfma_f32_32x32x16_bf16 v[50:65], v[142:145], v[148:151], v[50:65]
	v_mfma_f32_32x32x16_bf16 v[50:65], v[138:141], v[154:157], v[50:65]
	s_waitcnt lgkmcnt(8)
	ds_read_b64_tr_b16 v[148:149], v146 offset:52224
	ds_read_b64_tr_b16 v[150:151], v146 offset:56320
	ds_read_b64_tr_b16 v[154:155], v146 offset:60416
	ds_read_b64_tr_b16 v[156:157], v146 offset:64512
	v_mfma_f32_32x32x16_bf16 v[50:65], v[130:133], v[158:161], v[50:65]
	v_mfma_f32_32x32x16_bf16 v[50:65], v[134:137], v[232:235], v[50:65]
	s_waitcnt lgkmcnt(8)
	ds_read_b64_tr_b16 v[158:159], v152 offset:19456
	ds_read_b64_tr_b16 v[160:161], v152 offset:23552
	ds_read_b64_tr_b16 v[232:233], v152 offset:27648
	ds_read_b64_tr_b16 v[234:235], v152 offset:31744
	v_mfma_f32_32x32x16_bf16 v[34:49], v[142:145], v[236:239], v[34:49]
	v_mfma_f32_32x32x16_bf16 v[34:49], v[138:141], v[240:243], v[34:49]
	s_waitcnt lgkmcnt(8)
	ds_read_b64_tr_b16 v[236:237], v146 offset:52736
	ds_read_b64_tr_b16 v[238:239], v146 offset:56832
	ds_read_b64_tr_b16 v[240:241], v146 offset:60928
	ds_read_b64_tr_b16 v[242:243], v146 offset:65024
	v_mfma_f32_32x32x16_bf16 v[34:49], v[130:133], v[246:249], v[34:49]
	v_mfma_f32_32x32x16_bf16 v[34:49], v[134:137], v[250:253], v[34:49]
	s_waitcnt lgkmcnt(8)
	ds_read_b64_tr_b16 v[246:247], v152 offset:19968
	ds_read_b64_tr_b16 v[248:249], v152 offset:24064
	ds_read_b64_tr_b16 v[250:251], v152 offset:28160
	ds_read_b64_tr_b16 v[252:253], v152 offset:32256
	v_mfma_f32_32x32x16_bf16 v[18:33], v[142:145], v[148:151], v[18:33]
	v_mfma_f32_32x32x16_bf16 v[18:33], v[138:141], v[154:157], v[18:33]
	s_waitcnt lgkmcnt(8)
	v_mfma_f32_32x32x16_bf16 v[18:33], v[130:133], v[158:161], v[18:33]
	v_mfma_f32_32x32x16_bf16 v[18:33], v[134:137], v[232:235], v[18:33]
	s_waitcnt lgkmcnt(4)
	v_mfma_f32_32x32x16_bf16 v[2:17], v[142:145], v[236:239], v[2:17]
	v_mfma_f32_32x32x16_bf16 v[2:17], v[138:141], v[240:243], v[2:17]
	s_waitcnt lgkmcnt(0)
	v_mfma_f32_32x32x16_bf16 v[2:17], v[130:133], v[246:249], v[2:17]
	v_mfma_f32_32x32x16_bf16 v[2:17], v[134:137], v[250:253], v[2:17]
	s_setprio 0
	s_cbranch_scc0 .LBB0_1233
	s_cmp_ge_u32 s66, 0x80
	s_cbranch_scc1 .Lst1_b
	s_barrier

.Lst2_a:
.LBB0_1256:
	s_waitcnt vmcnt(6)
	s_waitcnt lgkmcnt(0)
	s_barrier
	s_setprio 1
	v_lshl_add_u32 v254, s4, 14, v218
	v_add_u32_e32 v255, v254, v226
	ds_read_b128 v[228:231], v255
	ds_read_b128 v[232:235], v255 offset:8192
	v_add_u32_e32 v255, v254, v225
	ds_read_b128 v[236:239], v255
	ds_read_b128 v[240:243], v255 offset:8192
	s_add_i32 s5, s4, 1
	s_cmp_lg_u32 s4, 2
	s_waitcnt lgkmcnt(2)
	v_add_u32_e32 v255, v254, v224
	ds_read_b128 v[246:249], v255
	ds_read_b128 v[250:253], v255 offset:8192
	v_mfma_f32_32x32x16_bf16 v[130:145], v[232:235], v[190:193], 0
	v_mfma_f32_32x32x16_bf16 v[146:161], v[228:231], v[190:193], 0
	s_waitcnt lgkmcnt(2)
	v_add_u32_e32 v255, v254, v223
	ds_read_b128 v[228:231], v255
	ds_read_b128 v[232:235], v255 offset:8192
	v_mfma_f32_32x32x16_bf16 v[130:145], v[240:243], v[186:189], v[130:145]
	v_mfma_f32_32x32x16_bf16 v[146:161], v[236:239], v[186:189], v[146:161]
	s_waitcnt lgkmcnt(2)
	v_add_u32_e32 v255, v254, v222
	ds_read_b128 v[236:239], v255
	ds_read_b128 v[240:243], v255 offset:8192
	v_mfma_f32_32x32x16_bf16 v[130:145], v[250:253], v[182:185], v[130:145]
	v_mfma_f32_32x32x16_bf16 v[146:161], v[246:249], v[182:185], v[146:161]
	s_waitcnt lgkmcnt(2)
	v_add_u32_e32 v255, v254, v221
	ds_read_b128 v[246:249], v255
	ds_read_b128 v[250:253], v255 offset:8192
	v_mfma_f32_32x32x16_bf16 v[130:145], v[232:235], v[178:181], v[130:145]
	v_mfma_f32_32x32x16_bf16 v[146:161], v[228:231], v[178:181], v[146:161]
	s_waitcnt lgkmcnt(2)
	v_add_u32_e32 v255, v254, v220
	ds_read_b128 v[228:231], v255
	ds_read_b128 v[232:235], v255 offset:8192
	v_mfma_f32_32x32x16_bf16 v[130:145], v[240:243], v[174:177], v[130:145]
	v_mfma_f32_32x32x16_bf16 v[146:161], v[236:239], v[174:177], v[146:161]
	s_waitcnt lgkmcnt(2)
	v_add_u32_e32 v255, v254, v219
	ds_read_b128 v[236:239], v255
	ds_read_b128 v[240:243], v255 offset:8192
	v_mfma_f32_32x32x16_bf16 v[130:145], v[250:253], v[170:173], v[130:145]
	v_mfma_f32_32x32x16_bf16 v[146:161], v[246:249], v[170:173], v[146:161]
	s_waitcnt lgkmcnt(2)
	v_mfma_f32_32x32x16_bf16 v[130:145], v[232:235], v[166:169], v[130:145]
	v_mfma_f32_32x32x16_bf16 v[146:161], v[228:231], v[166:169], v[146:161]
	s_waitcnt lgkmcnt(0)
	v_mfma_f32_32x32x16_bf16 v[130:145], v[240:243], v[162:165], v[130:145]
	v_mfma_f32_32x32x16_bf16 v[146:161], v[236:239], v[162:165], v[146:161]
	s_setprio 0
	s_nop 10
	v_fmamk_f32 v138, v138, 0x3e0293ee, v215
	v_fmamk_f32 v139, v139, 0x3e0293ee, v215
	v_fmamk_f32 v140, v140, 0x3e0293ee, v215
	v_fmamk_f32 v141, v141, 0x3e0293ee, v215
	v_fmamk_f32 v142, v142, 0x3e0293ee, v215
	v_exp_f32_e32 v227, v138
	v_fmamk_f32 v130, v130, 0x3e0293ee, v215
	v_fmamk_f32 v138, v155, 0x3e0293ee, v215
	v_exp_f32_e32 v155, v139
	v_fmamk_f32 v139, v156, 0x3e0293ee, v215
	v_exp_f32_e32 v156, v140
	v_fmamk_f32 v140, v157, 0x3e0293ee, v215
	v_exp_f32_e32 v157, v141
	v_fmamk_f32 v141, v158, 0x3e0293ee, v215
	v_exp_f32_e32 v158, v142
	v_fmamk_f32 v142, v159, 0x3e0293ee, v215
	v_fmamk_f32 v146, v146, 0x3e0293ee, v215
	v_exp_f32_e32 v159, v142
	v_fmamk_f32 v142, v143, 0x3e0293ee, v215
	v_exp_f32_e32 v146, v146
	v_fmamk_f32 v147, v147, 0x3e0293ee, v215
	v_exp_f32_e32 v228, v142
	v_fmamk_f32 v142, v160, 0x3e0293ee, v215
	v_exp_f32_e32 v147, v147
	v_fmamk_f32 v148, v148, 0x3e0293ee, v215
	v_exp_f32_e32 v160, v142
	v_fmamk_f32 v142, v144, 0x3e0293ee, v215
	v_exp_f32_e32 v148, v148
	v_fmamk_f32 v149, v149, 0x3e0293ee, v215
	v_exp_f32_e32 v229, v142
	v_fmamk_f32 v142, v161, 0x3e0293ee, v215
	v_exp_f32_e32 v149, v149
	v_fmamk_f32 v150, v150, 0x3e0293ee, v215
	v_exp_f32_e32 v161, v142
	v_fmamk_f32 v142, v145, 0x3e0293ee, v215
	v_exp_f32_e32 v150, v150
	v_fmamk_f32 v151, v151, 0x3e0293ee, v215
	v_exp_f32_e32 v230, v142
	v_add_f32_e32 v142, 0, v146
	v_exp_f32_e32 v151, v151
	v_fmamk_f32 v152, v152, 0x3e0293ee, v215
	v_add_f32_e32 v142, v147, v142
	v_exp_f32_e32 v152, v152
	v_fmamk_f32 v153, v153, 0x3e0293ee, v215
	v_add_f32_e32 v142, v148, v142
	v_exp_f32_e32 v153, v153
	v_fmamk_f32 v154, v154, 0x3e0293ee, v215
	v_add_f32_e32 v142, v149, v142
	v_exp_f32_e32 v154, v154
	v_add_f32_e32 v142, v150, v142
	v_exp_f32_e32 v138, v138
	v_add_f32_e32 v142, v151, v142
	v_exp_f32_e32 v139, v139
	v_add_f32_e32 v142, v152, v142
	v_exp_f32_e32 v140, v140
	v_add_f32_e32 v142, v153, v142
	v_exp_f32_e32 v141, v141
	v_add_f32_e32 v142, v154, v142
	v_add_f32_e32 v142, v138, v142
	v_add_f32_e32 v142, v139, v142
	v_add_f32_e32 v142, v140, v142
	v_exp_f32_e32 v130, v130
	v_fmamk_f32 v131, v131, 0x3e0293ee, v215
	v_add_f32_e32 v142, v141, v142
	v_exp_f32_e32 v131, v131
	v_fmamk_f32 v132, v132, 0x3e0293ee, v215
	v_add_f32_e32 v142, v159, v142
	v_exp_f32_e32 v132, v132
	v_fmamk_f32 v133, v133, 0x3e0293ee, v215
	v_add_f32_e32 v142, v160, v142
	v_exp_f32_e32 v133, v133
	v_fmamk_f32 v134, v134, 0x3e0293ee, v215
	v_add_f32_e32 v142, v161, v142
	v_exp_f32_e32 v134, v134
	v_fmamk_f32 v135, v135, 0x3e0293ee, v215
	v_add_f32_e32 v142, v130, v142
	v_exp_f32_e32 v135, v135
	v_fmamk_f32 v136, v136, 0x3e0293ee, v215
	v_add_f32_e32 v142, v131, v142
	v_exp_f32_e32 v136, v136
	v_fmamk_f32 v137, v137, 0x3e0293ee, v215
	v_add_f32_e32 v142, v132, v142
	v_exp_f32_e32 v137, v137
	v_add_f32_e32 v142, v133, v142
	v_add_f32_e32 v142, v134, v142
	v_add_f32_e32 v142, v135, v142
	v_add_f32_e32 v142, v136, v142
	v_add_f32_e32 v142, v137, v142
	v_add_f32_e32 v142, v227, v142
	v_add_f32_e32 v142, v155, v142
	v_add_f32_e32 v142, v156, v142
	v_add_f32_e32 v142, v157, v142
	v_add_f32_e32 v142, v158, v142
	v_add_f32_e32 v142, v228, v142
	v_add_f32_e32 v142, v229, v142
	v_add_f32_e32 v142, v230, v142
	v_mov_b32_e32 v143, v142
	s_nop 1
	v_permlane32_swap_b32_e32 v142, v143
	v_add_f32_e32 v142, v142, v143
	v_add_f32_e32 v211, v211, v142
	v_cvt_pk_bf16_f32 v142, v146, v147
	v_cvt_pk_bf16_f32 v143, v148, v149
	v_cvt_pk_bf16_f32 v144, v150, v151
	v_cvt_pk_bf16_f32 v145, v152, v153
	s_nop 0
	v_permlane32_swap_b32_e32 v142, v144
	v_permlane32_swap_b32_e32 v143, v145
	v_lshl_add_u32 v146, s4, 15, v217
	v_cvt_pk_bf16_f32 v138, v154, v138
	v_cvt_pk_bf16_f32 v139, v139, v140
	v_cvt_pk_bf16_f32 v140, v141, v159
	v_cvt_pk_bf16_f32 v141, v160, v161
	v_cvt_pk_bf16_f32 v130, v130, v131
	v_cvt_pk_bf16_f32 v131, v132, v133
	v_cvt_pk_bf16_f32 v132, v134, v135
	v_cvt_pk_bf16_f32 v133, v136, v137
	v_cvt_pk_bf16_f32 v134, v227, v155
	v_cvt_pk_bf16_f32 v135, v156, v157
	v_cvt_pk_bf16_f32 v136, v158, v228
	v_cvt_pk_bf16_f32 v137, v229, v230
	v_add_u32_e32 v152, 0xc000, v146
	s_waitcnt vmcnt(0)
	s_barrier
	s_add_i32 s98, s4, -1
	s_cmp_eq_u32 s4, 0
	s_cselect_b32 s98, 2, s98
	s_lshl_b32 s99, s98, 14
	s_add_i32 s99, s90, s99
	s_lshl_b32 s98, s98, 15
	s_add_i32 s98, s90, s98
	v_lshl_add_u64 v[236:237], v[194:195], 0, s[2:3]
	s_mov_b32 m0, s99
	s_nop 0
	global_load_lds_dwordx4 v[236:237], off
	v_lshl_add_u64 v[236:237], v[196:197], 0, s[2:3]
	s_add_i32 m0, s99, 0x2000
	s_nop 0
	global_load_lds_dwordx4 v[236:237], off
	v_lshl_add_u64 v[236:237], v[198:199], 0, s[2:3]
	s_add_i32 m0, s98, 0xc000
	s_nop 0
	global_load_lds_dwordx4 v[236:237], off
	v_lshl_add_u64 v[236:237], v[200:201], 0, s[2:3]
	s_add_i32 m0, s98, 0xe000
	s_nop 0
	global_load_lds_dwordx4 v[236:237], off
	v_lshl_add_u64 v[236:237], v[202:203], 0, s[2:3]
	s_add_i32 m0, s98, 0x10000
	s_nop 0
	global_load_lds_dwordx4 v[236:237], off
	v_lshl_add_u64 v[236:237], v[208:209], 0, s[2:3]
	s_add_i32 m0, s98, 0x12000
	s_nop 0
	global_load_lds_dwordx4 v[236:237], off
	s_cmp_lg_u32 s4, 2
	ds_read_b64_tr_b16 v[148:149], v146 offset:49152
	ds_read_b64_tr_b16 v[150:151], v146 offset:53248
	ds_read_b64_tr_b16 v[154:155], v146 offset:57344
	ds_read_b64_tr_b16 v[156:157], v146 offset:61440
	ds_read_b64_tr_b16 v[158:159], v152 offset:16384
	ds_read_b64_tr_b16 v[160:161], v152 offset:20480
	ds_read_b64_tr_b16 v[232:233], v152 offset:24576
	ds_read_b64_tr_b16 v[234:235], v152 offset:28672
	ds_read_b64_tr_b16 v[236:237], v146 offset:49664
	ds_read_b64_tr_b16 v[238:239], v146 offset:53760
	ds_read_b64_tr_b16 v[240:241], v146 offset:57856
	ds_read_b64_tr_b16 v[242:243], v146 offset:61952
	s_setprio 1
	s_waitcnt lgkmcnt(8)
	ds_read_b64_tr_b16 v[246:247], v152 offset:16896
	ds_read_b64_tr_b16 v[248:249], v152 offset:20992
	ds_read_b64_tr_b16 v[250:251], v152 offset:25088
	ds_read_b64_tr_b16 v[252:253], v152 offset:29184
	v_mfma_f32_32x32x16_bf16 v[114:129], v[142:145], v[148:151], v[114:129]
	v_permlane32_swap_b32_e32 v138, v140
	v_permlane32_swap_b32_e32 v139, v141
	v_permlane32_swap_b32_e32 v130, v132
	v_permlane32_swap_b32_e32 v131, v133
	v_mfma_f32_32x32x16_bf16 v[114:129], v[138:141], v[154:157], v[114:129]
	v_permlane32_swap_b32_e32 v134, v136
	v_permlane32_swap_b32_e32 v135, v137
	s_cselect_b32 s4, s5, 0
	s_add_u32 s2, s2, 0x100000
	s_addc_u32 s3, s3, 0
	s_waitcnt lgkmcnt(8)
	ds_read_b64_tr_b16 v[148:149], v146 offset:50176
	ds_read_b64_tr_b16 v[150:151], v146 offset:54272
	ds_read_b64_tr_b16 v[154:155], v146 offset:58368
	ds_read_b64_tr_b16 v[156:157], v146 offset:62464
	v_mfma_f32_32x32x16_bf16 v[114:129], v[130:133], v[158:161], v[114:129]
	v_mfma_f32_32x32x16_bf16 v[114:129], v[134:137], v[232:235], v[114:129]
	s_cmp_eq_u32 s2, 0x2200000
	s_waitcnt lgkmcnt(8)
	ds_read_b64_tr_b16 v[158:159], v152 offset:17408
	ds_read_b64_tr_b16 v[160:161], v152 offset:21504
	ds_read_b64_tr_b16 v[232:233], v152 offset:25600
	ds_read_b64_tr_b16 v[234:235], v152 offset:29696
	v_mfma_f32_32x32x16_bf16 v[98:113], v[142:145], v[236:239], v[98:113]
	v_mfma_f32_32x32x16_bf16 v[98:113], v[138:141], v[240:243], v[98:113]
	s_waitcnt lgkmcnt(8)
	ds_read_b64_tr_b16 v[236:237], v146 offset:50688
	ds_read_b64_tr_b16 v[238:239], v146 offset:54784
	ds_read_b64_tr_b16 v[240:241], v146 offset:58880
	ds_read_b64_tr_b16 v[242:243], v146 offset:62976
	v_mfma_f32_32x32x16_bf16 v[98:113], v[130:133], v[246:249], v[98:113]
	v_mfma_f32_32x32x16_bf16 v[98:113], v[134:137], v[250:253], v[98:113]
	s_waitcnt lgkmcnt(8)
	ds_read_b64_tr_b16 v[246:247], v152 offset:17920
	ds_read_b64_tr_b16 v[248:249], v152 offset:22016
	ds_read_b64_tr_b16 v[250:251], v152 offset:26112
	ds_read_b64_tr_b16 v[252:253], v152 offset:30208
	v_mfma_f32_32x32x16_bf16 v[82:97], v[142:145], v[148:151], v[82:97]
	v_mfma_f32_32x32x16_bf16 v[82:97], v[138:141], v[154:157], v[82:97]
	s_waitcnt lgkmcnt(8)
	ds_read_b64_tr_b16 v[148:149], v146 offset:51200
	ds_read_b64_tr_b16 v[150:151], v146 offset:55296
	ds_read_b64_tr_b16 v[154:155], v146 offset:59392
	ds_read_b64_tr_b16 v[156:157], v146 offset:63488
	v_mfma_f32_32x32x16_bf16 v[82:97], v[130:133], v[158:161], v[82:97]
	v_mfma_f32_32x32x16_bf16 v[82:97], v[134:137], v[232:235], v[82:97]
	s_waitcnt lgkmcnt(8)
	ds_read_b64_tr_b16 v[158:159], v152 offset:18432
	ds_read_b64_tr_b16 v[160:161], v152 offset:22528
	ds_read_b64_tr_b16 v[232:233], v152 offset:26624
	ds_read_b64_tr_b16 v[234:235], v152 offset:30720
	v_mfma_f32_32x32x16_bf16 v[66:81], v[142:145], v[236:239], v[66:81]
	v_mfma_f32_32x32x16_bf16 v[66:81], v[138:141], v[240:243], v[66:81]
	s_waitcnt lgkmcnt(8)
	ds_read_b64_tr_b16 v[236:237], v146 offset:51712
	ds_read_b64_tr_b16 v[238:239], v146 offset:55808
	ds_read_b64_tr_b16 v[240:241], v146 offset:59904
	ds_read_b64_tr_b16 v[242:243], v146 offset:64000
	v_mfma_f32_32x32x16_bf16 v[66:81], v[130:133], v[246:249], v[66:81]
	v_mfma_f32_32x32x16_bf16 v[66:81], v[134:137], v[250:253], v[66:81]
	s_waitcnt lgkmcnt(8)
	ds_read_b64_tr_b16 v[246:247], v152 offset:18944
	ds_read_b64_tr_b16 v[248:249], v152 offset:23040
	ds_read_b64_tr_b16 v[250:251], v152 offset:27136
	ds_read_b64_tr_b16 v[252:253], v152 offset:31232
	v_mfma_f32_32x32x16_bf16 v[50:65], v[142:145], v[148:151], v[50:65]
	v_mfma_f32_32x32x16_bf16 v[50:65], v[138:141], v[154:157], v[50:65]
	s_waitcnt lgkmcnt(8)
	ds_read_b64_tr_b16 v[148:149], v146 offset:52224
	ds_read_b64_tr_b16 v[150:151], v146 offset:56320
	ds_read_b64_tr_b16 v[154:155], v146 offset:60416
	ds_read_b64_tr_b16 v[156:157], v146 offset:64512
	v_mfma_f32_32x32x16_bf16 v[50:65], v[130:133], v[158:161], v[50:65]
	v_mfma_f32_32x32x16_bf16 v[50:65], v[134:137], v[232:235], v[50:65]
	s_waitcnt lgkmcnt(8)
	ds_read_b64_tr_b16 v[158:159], v152 offset:19456
	ds_read_b64_tr_b16 v[160:161], v152 offset:23552
	ds_read_b64_tr_b16 v[232:233], v152 offset:27648
	ds_read_b64_tr_b16 v[234:235], v152 offset:31744
	v_mfma_f32_32x32x16_bf16 v[34:49], v[142:145], v[236:239], v[34:49]
	v_mfma_f32_32x32x16_bf16 v[34:49], v[138:141], v[240:243], v[34:49]
	s_waitcnt lgkmcnt(8)
	ds_read_b64_tr_b16 v[236:237], v146 offset:52736
	ds_read_b64_tr_b16 v[238:239], v146 offset:56832
	ds_read_b64_tr_b16 v[240:241], v146 offset:60928
	ds_read_b64_tr_b16 v[242:243], v146 offset:65024
	v_mfma_f32_32x32x16_bf16 v[34:49], v[130:133], v[246:249], v[34:49]
	v_mfma_f32_32x32x16_bf16 v[34:49], v[134:137], v[250:253], v[34:49]
	s_waitcnt lgkmcnt(8)
	ds_read_b64_tr_b16 v[246:247], v152 offset:19968
	ds_read_b64_tr_b16 v[248:249], v152 offset:24064
	ds_read_b64_tr_b16 v[250:251], v152 offset:28160
	ds_read_b64_tr_b16 v[252:253], v152 offset:32256
	v_mfma_f32_32x32x16_bf16 v[18:33], v[142:145], v[148:151], v[18:33]
	v_mfma_f32_32x32x16_bf16 v[18:33], v[138:141], v[154:157], v[18:33]
	s_waitcnt lgkmcnt(8)
	v_mfma_f32_32x32x16_bf16 v[18:33], v[130:133], v[158:161], v[18:33]
	v_mfma_f32_32x32x16_bf16 v[18:33], v[134:137], v[232:235], v[18:33]
	s_waitcnt lgkmcnt(4)
	v_mfma_f32_32x32x16_bf16 v[2:17], v[142:145], v[236:239], v[2:17]
	v_mfma_f32_32x32x16_bf16 v[2:17], v[138:141], v[240:243], v[2:17]
	s_waitcnt lgkmcnt(0)
	v_mfma_f32_32x32x16_bf16 v[2:17], v[130:133], v[246:249], v[2:17]
	v_mfma_f32_32x32x16_bf16 v[2:17], v[134:137], v[250:253], v[2:17]
	s_setprio 0
	s_cbranch_scc0 .LBB0_1256
	s_cmp_ge_u32 s66, 0x80
	s_cbranch_scc1 .Lst2_b
	s_barrier
